# out-proj / MLP-out prologues too: counted wait vmcnt(8) so all seven stage groups are in flight together
# baseline (speedup 1.0000x reference)
; __device__ __forceinline__ int prow0(int pm) { return (pm >> 4) * LP + PADR + (pm & 15) * 256; }
;     __device__ __forceinline__ void prep(int pm, int par, LAS unsigned char* lds) const { if (fold) prep_rowstats(stat, pm, par, lds); }
;     __device__ __forceinline__ void prep(int pm, int par, LAS unsigned char* lds) const { if (!ident) prep_rowstats(stat, pm, par, lds); }
;     __device__ __forceinline__ void prep(int pm, int par, LAS unsigned char* lds) const { prep_rowstats(stat, pm, par, lds); }
; #define G_STAGE(bufoff, gbase) do { _Pragma("unroll") for (int _i = 0; _i < 2; ++_i) \
;         __builtin_amdgcn_global_load_lds((const unsigned*)((const char*)(gbase) + voff[_i]), (LAS unsigned*)(lds + (bufoff) + ldsw + _i * 8192), 16, 0, 0); } while (0)
; #define G_WAIT_V(n) asm volatile("s_waitcnt vmcnt(" #n ")" ::: "memory")
; #define G_BAR __builtin_amdgcn_s_barrier()
; template <class Epi>
; __device__ __forceinline__ void gemm_phase(LAS unsigned char* lds, const bf16_t* Ag, const bf16_t* Btg, const int K, const int nM, const int nN, const Epi& E) {
;     ...
;     for (int i = 0; i < 2; ++i) { int R, C; stage_rc(tid * 16 + i * 8192, R, C); voff[i] = (unsigned)(R * K + C) * 2u; }
;     const size_t kstep = 128, hstep = (size_t)128 * K * 2, tstep = 2 * hstep;
;     const unsigned ldsw = (unsigned)wid * 1024u;
;     const int aoff = lds_byte(wr * 64 + fr, fq * 8), boff = lds_byte(wc * 32 + fr, fq * 8);
;     ...
;     const size_t rstep = (size_t)K * 2;
;     const char* cA = (const char*)Ag + (size_t)prow0(pm) * rstep; const char* cB = (const char*)Btg + (size_t)pn * tstep;
;     E.prep(pm, par, lds);
;     G_STAGE(G_SB(0, 0), cB); G_STAGE(G_SA(0, 0), cA); G_STAGE(G_SB(0, 1), cB + hstep); G_STAGE(G_SA(0, 1), cA + hstep);
;     if (wr == 1) G_BAR;
;     G_WAIT_V(4); G_BAR;
;     G_STAGE(G_SB(1, 0), cB + kstep); G_STAGE(G_SA(1, 0), cA + kstep); G_STAGE(G_SB(1, 1), cB + hstep + kstep);
;     G_WAIT_V(6); G_BAR;
.LBB0_144:
	s_waitcnt vmcnt(8)
	v_bfe_u32 v26, v8, 4, 2
	v_lshl_add_u64 v[18:19], s[66:67], 0, v[0:1]
	v_mov_b32_e32 v3, v1
	v_and_b32_e32 v17, 15, v8
	v_lshlrev_b32_e32 v27, 4, v26
	v_lshlrev_b32_e32 v8, 2, v8
	v_lshl_add_u64 v[20:21], s[66:67], 0, v[2:3]
	s_and_b32 s90, s14, 3
	s_lshl_b32 s26, s12, 6
	v_lshl_or_b32 v27, v17, 6, v27
	s_lshl_b32 s12, s12, 13
	v_and_b32_e32 v8, 32, v8
	s_add_i32 m0, s72, 0x18000
	v_lshl_add_u64 v[18:19], v[18:19], 0, s[94:95]
	v_lshl_add_u64 v[22:23], s[64:65], 0, v[0:1]
	v_bitop3_b32 v28, v27, s12, v8 bitop3:0xde
	s_lshl_b32 s12, s90, 12
	s_barrier
	global_load_lds_dwordx4 v[18:19], off
	v_lshl_add_u64 v[18:19], v[20:21], 0, s[94:95]
	s_add_i32 m0, s72, 0x1a000
	s_add_i32 s76, s72, 0x8000
	s_add_i32 s77, s72, 0xa000
	v_lshl_add_u64 v[24:25], s[64:65], 0, v[2:3]
	global_load_lds_dwordx4 v[18:19], off
	v_lshl_add_u64 v[18:19], v[22:23], 0, s[94:95]
	s_mov_b32 m0, s76
	s_add_u32 s14, s66, 0x40080
	global_load_lds_dwordx4 v[18:19], off
	v_lshl_add_u64 v[18:19], v[24:25], 0, s[94:95]
	s_mov_b32 m0, s77
	s_addc_u32 s15, s67, 0
	global_load_lds_dwordx4 v[18:19], off
	s_add_i32 m0, s72, 0x1c000
	v_lshl_add_u64 v[18:19], s[14:15], 0, v[0:1]
	global_load_lds_dwordx4 v[18:19], off
	v_lshl_add_u64 v[18:19], s[14:15], 0, v[2:3]
	s_add_i32 m0, s72, 0x1e000
	v_bitop3_b32 v179, v27, s12, v8 bitop3:0xde
	global_load_lds_dwordx4 v[18:19], off
	v_lshlrev_b32_e32 v8, 2, v26
	v_lshl_or_b32 v222, s90, 5, v8
	v_lshlrev_b32_e32 v8, 13, v13
	v_and_b32_e32 v8, 0x7fffc000, v8
	v_lshl_add_u32 v8, v14, 10, v8
	v_or_b32_e32 v8, v8, v15
	v_add_lshl_u32 v14, v8, v16, 1
	v_lshlrev_b32_e32 v8, 13, v9
	v_and_b32_e32 v8, 0x7fffc000, v8
	v_lshl_add_u32 v8, v10, 10, v8
	v_or_b32_e32 v8, v8, v11
	v_mov_b32_e32 v15, v1
	s_mov_b64 s[14:15], 0x40080
	v_add_lshl_u32 v8, v8, v12, 1
	v_mov_b32_e32 v9, v1
	v_lshl_add_u64 v[136:137], v[14:15], 0, s[14:15]
	v_lshl_add_u64 v[138:139], v[8:9], 0, s[14:15]
	v_readlane_b32 s14, v253, 51
	v_or_b32_e32 v176, s26, v17
	s_waitcnt vmcnt(6)
	s_addk_i32 s26, 0x80
	v_readlane_b32 s15, v253, 52
	v_or_b32_e32 v226, s26, v17
	s_mov_b32 s97, s14
	v_readlane_b32 s14, v255, 21
	v_cmp_eq_u32_e64 s[44:45], 0, v26
	v_or_b32_e32 v223, 16, v176
	v_or_b32_e32 v224, 32, v176
	v_or_b32_e32 v225, 48, v176
	v_or_b32_e32 v227, 16, v226
	v_or_b32_e32 v228, 32, v226
	v_or_b32_e32 v229, 48, v226
	v_mov_b32_e32 v231, 0
	v_add_u32_e32 v230, 0, v28
	v_readlane_b32 s96, v253, 27
	s_mov_b32 s78, s14
	s_barrier
	v_readlane_b32 s15, v255, 22
	s_branch .LBB0_147

; __device__ __forceinline__ int prow0(int pm) { return (pm >> 4) * LP + PADR + (pm & 15) * 256; }
;     __device__ __forceinline__ void prep(int pm, int par, LAS unsigned char* lds) const { if (fold) prep_rowstats(stat, pm, par, lds); }
;     __device__ __forceinline__ void prep(int pm, int par, LAS unsigned char* lds) const { if (!ident) prep_rowstats(stat, pm, par, lds); }
;     __device__ __forceinline__ void prep(int pm, int par, LAS unsigned char* lds) const { prep_rowstats(stat, pm, par, lds); }
; #define G_STAGE(bufoff, gbase) do { _Pragma("unroll") for (int _i = 0; _i < 2; ++_i) \
;         __builtin_amdgcn_global_load_lds((const unsigned*)((const char*)(gbase) + voff[_i]), (LAS unsigned*)(lds + (bufoff) + ldsw + _i * 8192), 16, 0, 0); } while (0)
; #define G_WAIT_V(n) asm volatile("s_waitcnt vmcnt(" #n ")" ::: "memory")
; #define G_BAR __builtin_amdgcn_s_barrier()
; template <class Epi>
; __device__ __forceinline__ void gemm_phase(LAS unsigned char* lds, const bf16_t* Ag, const bf16_t* Btg, const int K, const int nM, const int nN, const Epi& E) {
;     ...
;     for (int i = 0; i < 2; ++i) { int R, C; stage_rc(tid * 16 + i * 8192, R, C); voff[i] = (unsigned)(R * K + C) * 2u; }
;     const size_t kstep = 128, hstep = (size_t)128 * K * 2, tstep = 2 * hstep;
;     const unsigned ldsw = (unsigned)wid * 1024u;
;     const int aoff = lds_byte(wr * 64 + fr, fq * 8), boff = lds_byte(wc * 32 + fr, fq * 8);
;     ...
;     const size_t rstep = (size_t)K * 2;
;     const char* cA = (const char*)Ag + (size_t)prow0(pm) * rstep; const char* cB = (const char*)Btg + (size_t)pn * tstep;
;     E.prep(pm, par, lds);
;     G_STAGE(G_SB(0, 0), cB); G_STAGE(G_SA(0, 0), cA); G_STAGE(G_SB(0, 1), cB + hstep); G_STAGE(G_SA(0, 1), cA + hstep);
;     if (wr == 1) G_BAR;
;     G_WAIT_V(4); G_BAR;
;     G_STAGE(G_SB(1, 0), cB + kstep); G_STAGE(G_SA(1, 0), cA + kstep); G_STAGE(G_SB(1, 1), cB + hstep + kstep);
;     G_WAIT_V(6); G_BAR;
.LBB0_736:
	s_waitcnt vmcnt(8)
	v_bfe_u32 v26, v9, 4, 2
	v_lshl_add_u64 v[18:19], s[58:59], 0, v[0:1]
	v_mov_b32_e32 v3, v1
	v_and_b32_e32 v17, 15, v9
	v_lshlrev_b32_e32 v27, 4, v26
	v_lshlrev_b32_e32 v9, 2, v9
	v_lshl_add_u64 v[20:21], s[58:59], 0, v[2:3]
	s_and_b32 s90, s14, 3
	s_lshl_b32 s24, s12, 6
	v_lshl_or_b32 v27, v17, 6, v27
	s_lshl_b32 s12, s12, 13
	v_and_b32_e32 v9, 32, v9
	s_add_i32 m0, s66, 0x18000
	v_lshl_add_u64 v[18:19], v[18:19], 0, s[94:95]
	v_lshl_add_u64 v[22:23], s[56:57], 0, v[0:1]
	v_bitop3_b32 v28, v27, s12, v9 bitop3:0xde
	s_lshl_b32 s12, s90, 12
	s_barrier
	global_load_lds_dwordx4 v[18:19], off
	v_lshl_add_u64 v[18:19], v[20:21], 0, s[94:95]
	s_add_i32 m0, s66, 0x1a000
	s_add_i32 s70, s66, 0x8000
	s_add_i32 s71, s66, 0xa000
	v_lshl_add_u64 v[24:25], s[56:57], 0, v[2:3]
	global_load_lds_dwordx4 v[18:19], off
	v_lshl_add_u64 v[18:19], v[22:23], 0, s[94:95]
	s_mov_b32 m0, s70
	s_add_u32 s14, s58, 0x100080
	global_load_lds_dwordx4 v[18:19], off
	v_lshl_add_u64 v[18:19], v[24:25], 0, s[94:95]
	s_mov_b32 m0, s71
	s_addc_u32 s15, s59, 0
	global_load_lds_dwordx4 v[18:19], off
	s_add_i32 m0, s66, 0x1c000
	v_lshl_add_u64 v[18:19], s[14:15], 0, v[0:1]
	global_load_lds_dwordx4 v[18:19], off
	v_lshl_add_u64 v[18:19], s[14:15], 0, v[2:3]
	s_add_i32 m0, s66, 0x1e000
	v_bitop3_b32 v165, v27, s12, v9 bitop3:0xde
	global_load_lds_dwordx4 v[18:19], off
	v_lshlrev_b32_e32 v9, 2, v26
	v_lshl_or_b32 v166, s90, 5, v9
	v_lshlrev_b32_e32 v9, 15, v13
	v_lshlrev_b32_e32 v8, 15, v8
	v_and_b32_e32 v9, 0x7fff0000, v9
	v_and_b32_e32 v8, 0x7fff0000, v8
	v_lshl_add_u32 v9, v14, 12, v9
	v_lshl_add_u32 v8, v10, 12, v8
	v_or_b32_e32 v9, v9, v15
	v_or_b32_e32 v8, v8, v11
	v_add_lshl_u32 v14, v9, v16, 1
	v_mov_b32_e32 v15, v1
	s_mov_b64 s[14:15], 0x100080
	v_add_lshl_u32 v8, v8, v12, 1
	v_mov_b32_e32 v9, v1
	v_lshl_add_u64 v[136:137], v[14:15], 0, s[14:15]
	v_lshl_add_u64 v[138:139], v[8:9], 0, s[14:15]
	v_readlane_b32 s14, v253, 51
	v_or_b32_e32 v164, s24, v17
	s_waitcnt vmcnt(6)
	s_addk_i32 s24, 0x80
	v_readlane_b32 s15, v253, 52
	v_or_b32_e32 v170, s24, v17
	s_mov_b32 s76, s14
	v_readlane_b32 s14, v255, 21
	s_mov_b32 s72, 0
	v_cmp_eq_u32_e64 s[44:45], 0, v26
	v_or_b32_e32 v167, 16, v164
	v_or_b32_e32 v168, 32, v164
	v_or_b32_e32 v169, 48, v164
	v_or_b32_e32 v171, 16, v170
	v_or_b32_e32 v172, 32, v170
	v_or_b32_e32 v173, 48, v170
	v_add_u32_e32 v174, 0, v28
	v_readlane_b32 s74, v253, 27
	s_mov_b32 s73, s14
	s_barrier
	v_readlane_b32 s15, v255, 22
	s_branch .LBB0_738
